# compress phase: W2 matmul loop issues its 10 LDS reads up front with counted lgkmcnt waits (was 8 serialized round trips per 8 steps), plus k-loop fragment read batching
# baseline (speedup 1.0000x reference)
; __device__ __forceinline__ unsigned pk2(float lo, float hi) { return pg8::cvt_pk_bf16(lo, hi); }
; __device__ __forceinline__ void compress_phase(const bf16* P, const bf16* W1T  , const float* cmpb  , const float* W2  ,
;                                                bf16* kcmp, bf16* vcmpT, lds_u8* lds, int G, int bid, int tid) {
;     ...
;             const int row = tid >> 4, d4 = tid & 15;
;             f32x4 o = {0.f, 0.f, 0.f, 0.f};
; #pragma unroll 8
;             for (int j = 0; j < 256; ++j) o += w2l[j * 16 + d4] * hid[row * 260 + j];
;             const int nn = nb * 32 + row;
;             if (nn >= 511) o = (f32x4){0.f, 0.f, 0.f, 0.f};
;             if (kv == 0) { u32x2 w; w.x = pk2(o.x, o.y); w.y = pk2(o.z, o.w); *(u32x2*)(kcmp + ((size_t)b * 512 + nn) * 256 + g * 64 + d4 * 4) = w; }
;             else {
; #pragma unroll
;                 for (int j = 0; j < 4; ++j) vcmpT[((size_t)b * 256 + g * 64 + d4 * 4 + j) * 512 + nn] = (bf16)(pk2(o[j], 0.f) & 0xffffu);
;             }
.LBB0_656:
	v_add_u32_e32 v18, 0, v2
	v_add_u32_e32 v9, 0, v8
	v_add_u32_e32 v14, 0x10800, v18
	v_add_u32_e32 v10, 0x10810, v18
	ds_read_b128 v[14:17], v14
	ds_read_b128 v[184:187], v10
	ds_read_b128 v[204:207], v9
	ds_read_b128 v[208:211], v9 offset:256
	ds_read_b128 v[212:215], v9 offset:512
	ds_read_b128 v[216:219], v9 offset:768
	ds_read_b128 v[236:239], v9 offset:1024
	ds_read_b128 v[240:243], v9 offset:1280
	ds_read_b128 v[244:247], v9 offset:1536
	ds_read_b128 v[248:251], v9 offset:1792
	s_add_i32 s20, s20, -8
	v_add_u32_e32 v8, 0x800, v8
	v_add_u32_e32 v2, 32, v2
	s_waitcnt lgkmcnt(7)
	v_pk_fma_f32 v[4:5], v[204:205], v[14:15], v[4:5] op_sel_hi:[1,0,1]
	v_pk_fma_f32 v[6:7], v[206:207], v[14:15], v[6:7] op_sel_hi:[1,0,1]
	s_waitcnt lgkmcnt(6)
	v_pk_fma_f32 v[4:5], v[208:209], v[14:15], v[4:5] op_sel:[0,1,0]
	v_pk_fma_f32 v[6:7], v[210:211], v[14:15], v[6:7] op_sel:[0,1,0]
	s_waitcnt lgkmcnt(5)
	v_pk_fma_f32 v[4:5], v[212:213], v[16:17], v[4:5] op_sel_hi:[1,0,1]
	v_pk_fma_f32 v[6:7], v[214:215], v[16:17], v[6:7] op_sel_hi:[1,0,1]
	s_waitcnt lgkmcnt(4)
	v_pk_fma_f32 v[4:5], v[216:217], v[16:17], v[4:5] op_sel:[0,1,0]
	v_pk_fma_f32 v[6:7], v[218:219], v[16:17], v[6:7] op_sel:[0,1,0]
	s_waitcnt lgkmcnt(3)
	v_pk_fma_f32 v[4:5], v[236:237], v[184:185], v[4:5] op_sel_hi:[1,0,1]
	v_pk_fma_f32 v[6:7], v[238:239], v[184:185], v[6:7] op_sel_hi:[1,0,1]
	s_waitcnt lgkmcnt(2)
	v_pk_fma_f32 v[4:5], v[240:241], v[184:185], v[4:5] op_sel:[0,1,0]
	v_pk_fma_f32 v[6:7], v[242:243], v[184:185], v[6:7] op_sel:[0,1,0]
	s_waitcnt lgkmcnt(1)
	v_pk_fma_f32 v[4:5], v[244:245], v[186:187], v[4:5] op_sel_hi:[1,0,1]
	v_pk_fma_f32 v[6:7], v[246:247], v[186:187], v[6:7] op_sel_hi:[1,0,1]
	s_waitcnt lgkmcnt(0)
	v_pk_fma_f32 v[4:5], v[248:249], v[186:187], v[4:5] op_sel:[0,1,0]
	v_pk_fma_f32 v[6:7], v[250:251], v[186:187], v[6:7] op_sel:[0,1,0]
	s_cmp_eq_u32 s20, 0
	s_cbranch_scc0 .LBB0_656
	v_lshl_add_u32 v8, s29, 5, v131
	s_movk_i32 s20, 0x1ff
	v_cmp_gt_i32_e32 vcc, s20, v8
	s_mov_b64 s[20:21], -1
	s_cmpk_lt_u32 s26, 0x80
	v_cndmask_b32_e32 v7, 0, v7, vcc
	v_cndmask_b32_e32 v6, 0, v6, vcc
	v_cndmask_b32_e32 v5, 0, v5, vcc
	v_cndmask_b32_e32 v4, 0, v4, vcc
	v_ashrrev_i32_e32 v9, 31, v8
	s_cbranch_scc1 .LBB0_659
	v_lshl_or_b32 v2, s27, 8, v86
	v_readlane_b32 s20, v252, 58
	v_or_b32_e32 v2, s28, v2
	v_readlane_b32 s21, v252, 59
	v_lshlrev_b32_e32 v2, 10, v2
	v_cvt_pk_bf16_f32 v12, v4, v3
	s_nop 0
	v_lshl_add_u64 v[10:11], v[8:9], 1, s[20:21]
	v_lshl_add_u64 v[10:11], v[10:11], 0, v[2:3]
	global_store_short v[10:11], v12, off
	v_cvt_pk_bf16_f32 v2, v5, v3
	global_store_short v[10:11], v2, off offset:1024
	v_cvt_pk_bf16_f32 v2, v6, v3
	s_mov_b64 s[20:21], 0
	global_store_short v[10:11], v2, off offset:2048
	v_cvt_pk_bf16_f32 v2, v7, v3
	global_store_short v[10:11], v2, off offset:3072
